# input-projection GEMM epilogue: straight-line fast path for tiles without aux columns (32-bit row offsets, permlane16 swap + 16 dwordx4 stores instead of 32 guarded dwordx2)
# speedup vs baseline: 1.0107x; 1.0078x over previous
; template <int EPI>
; DI void gemm_unit(const GemmP& g, int pm, int pn) {
;     ...
;     for (int ai = 0; ai < 2; ++ai)
; #pragma unroll
;       for (int m = 0; m < 4; ++m) {
;         const int row = row0 + ai * 128 + m * 16;
; #pragma unroll
;         for (int bj = 0; bj < 2; ++bj)
; #pragma unroll
;           for (int n = 0; n < 2; ++n) {
;             const int col = colb + bj * 128 + n * 16;
;             f32x4 v = acc[ai][bj][m][n];
;             if (EPI == EPI_BF16) {
;               if (col >= g.aux_n0) {
;                 const int c2 = col - g.aux_n0;
;                 if (c2 < g.aux_cnt) *(f32x4*)(g.aux + (size_t)row * 16 + c2) = v * g.aux_scale;
;               } else {
;                 if (g.colscale) v = v * *(const f32x4*)(g.colscale + col);
;                 uint2 o; o.x = pk2(v[0], v[1]); o.y = pk2(v[2], v[3]);
;                 *(uint2*)(g.Cb + (size_t)row * g.ldc + col) = o;
.LBB0_1028:
	s_or_b64 exec, exec, s[10:11]
	s_or_b32 s7, s8, 0xff
	s_cmp_lt_i32 s7, s39
	s_cbranch_scc0 .Lep0_slow
	v_or_b32_e32 v131, s6, v142
	v_add_u32_e32 v132, v131, v145
	v_lshlrev_b32_e32 v0, 5, v143
	v_lshlrev_b32_e32 v130, 2, v144
	v_or3_b32 v130, v0, v130, s8
	v_and_b32_e32 v133, 1, v144
	v_mul_u32_u24_e32 v133, 40, v133
	v_sub_u32_e32 v133, 32, v133
	v_lshl_add_u32 v130, v130, 1, v133
	s_movk_i32 s7, 0x2a00
	v_mad_u32_u24 v130, v132, s7, v130
	v_cvt_pk_bf16_f32 v122, v122, v123
	v_cvt_pk_bf16_f32 v123, v124, v125
	v_cvt_pk_bf16_f32 v124, v126, v127
	v_cvt_pk_bf16_f32 v125, v128, v129
	v_cvt_pk_bf16_f32 v114, v114, v115
	v_cvt_pk_bf16_f32 v115, v116, v117
	v_cvt_pk_bf16_f32 v116, v118, v119
	v_cvt_pk_bf16_f32 v117, v120, v121
	s_nop 0
	v_permlane16_swap_b32_e32 v122, v124
	v_permlane16_swap_b32_e32 v123, v125
	v_permlane16_swap_b32_e32 v114, v116
	v_permlane16_swap_b32_e32 v115, v117
	s_nop 0
	global_store_dwordx4 v130, v[122:125], s[18:19]
	global_store_dwordx4 v130, v[114:117], s[18:19] offset:256
	v_cvt_pk_bf16_f32 v106, v106, v107
	v_cvt_pk_bf16_f32 v107, v108, v109
	v_cvt_pk_bf16_f32 v108, v110, v111
	v_cvt_pk_bf16_f32 v109, v112, v113
	v_cvt_pk_bf16_f32 v98, v98, v99
	v_cvt_pk_bf16_f32 v99, v100, v101
	v_cvt_pk_bf16_f32 v100, v102, v103
	v_cvt_pk_bf16_f32 v101, v104, v105
	v_add_u32_e32 v133, 0x2a000, v130
	v_permlane16_swap_b32_e32 v106, v108
	v_permlane16_swap_b32_e32 v107, v109
	v_permlane16_swap_b32_e32 v98, v100
	v_permlane16_swap_b32_e32 v99, v101
	s_nop 0
	global_store_dwordx4 v133, v[106:109], s[18:19]
	global_store_dwordx4 v133, v[98:101], s[18:19] offset:256
	v_cvt_pk_bf16_f32 v90, v90, v91
	v_cvt_pk_bf16_f32 v91, v92, v93
	v_cvt_pk_bf16_f32 v92, v94, v95
	v_cvt_pk_bf16_f32 v93, v96, v97
	v_cvt_pk_bf16_f32 v82, v82, v83
	v_cvt_pk_bf16_f32 v83, v84, v85
	v_cvt_pk_bf16_f32 v84, v86, v87
	v_cvt_pk_bf16_f32 v85, v88, v89
	v_add_u32_e32 v133, 0x54000, v130
	v_permlane16_swap_b32_e32 v90, v92
	v_permlane16_swap_b32_e32 v91, v93
	v_permlane16_swap_b32_e32 v82, v84
	v_permlane16_swap_b32_e32 v83, v85
	s_nop 0
	global_store_dwordx4 v133, v[90:93], s[18:19]
	global_store_dwordx4 v133, v[82:85], s[18:19] offset:256
	v_cvt_pk_bf16_f32 v74, v74, v75
	v_cvt_pk_bf16_f32 v75, v76, v77
	v_cvt_pk_bf16_f32 v76, v78, v79
	v_cvt_pk_bf16_f32 v77, v80, v81
	v_cvt_pk_bf16_f32 v66, v66, v67
	v_cvt_pk_bf16_f32 v67, v68, v69
	v_cvt_pk_bf16_f32 v68, v70, v71
	v_cvt_pk_bf16_f32 v69, v72, v73
	v_add_u32_e32 v133, 0x7e000, v130
	v_permlane16_swap_b32_e32 v74, v76
	v_permlane16_swap_b32_e32 v75, v77
	v_permlane16_swap_b32_e32 v66, v68
	v_permlane16_swap_b32_e32 v67, v69
	s_nop 0
	global_store_dwordx4 v133, v[74:77], s[18:19]
	global_store_dwordx4 v133, v[66:69], s[18:19] offset:256
	v_cvt_pk_bf16_f32 v58, v58, v59
	v_cvt_pk_bf16_f32 v59, v60, v61
	v_cvt_pk_bf16_f32 v60, v62, v63
	v_cvt_pk_bf16_f32 v61, v64, v65
	v_cvt_pk_bf16_f32 v50, v50, v51
	v_cvt_pk_bf16_f32 v51, v52, v53
	v_cvt_pk_bf16_f32 v52, v54, v55
	v_cvt_pk_bf16_f32 v53, v56, v57
	v_add_u32_e32 v133, 0x150000, v130
	v_permlane16_swap_b32_e32 v58, v60
	v_permlane16_swap_b32_e32 v59, v61
	v_permlane16_swap_b32_e32 v50, v52
	v_permlane16_swap_b32_e32 v51, v53
	s_nop 0
	global_store_dwordx4 v133, v[58:61], s[18:19]
	global_store_dwordx4 v133, v[50:53], s[18:19] offset:256
	v_cvt_pk_bf16_f32 v42, v42, v43
	v_cvt_pk_bf16_f32 v43, v44, v45
	v_cvt_pk_bf16_f32 v44, v46, v47
	v_cvt_pk_bf16_f32 v45, v48, v49
	v_cvt_pk_bf16_f32 v34, v34, v35
	v_cvt_pk_bf16_f32 v35, v36, v37
	v_cvt_pk_bf16_f32 v36, v38, v39
	v_cvt_pk_bf16_f32 v37, v40, v41
	v_add_u32_e32 v133, 0x17a000, v130
	v_permlane16_swap_b32_e32 v42, v44
	v_permlane16_swap_b32_e32 v43, v45
	v_permlane16_swap_b32_e32 v34, v36
	v_permlane16_swap_b32_e32 v35, v37
	s_nop 0
	global_store_dwordx4 v133, v[42:45], s[18:19]
	global_store_dwordx4 v133, v[34:37], s[18:19] offset:256
	v_cvt_pk_bf16_f32 v26, v26, v27
	v_cvt_pk_bf16_f32 v27, v28, v29
	v_cvt_pk_bf16_f32 v28, v30, v31
	v_cvt_pk_bf16_f32 v29, v32, v33
	v_cvt_pk_bf16_f32 v18, v18, v19
	v_cvt_pk_bf16_f32 v19, v20, v21
	v_cvt_pk_bf16_f32 v20, v22, v23
	v_cvt_pk_bf16_f32 v21, v24, v25
	v_add_u32_e32 v133, 0x1a4000, v130
	v_permlane16_swap_b32_e32 v26, v28
	v_permlane16_swap_b32_e32 v27, v29
	v_permlane16_swap_b32_e32 v18, v20
	v_permlane16_swap_b32_e32 v19, v21
	s_nop 0
	global_store_dwordx4 v133, v[26:29], s[18:19]
	global_store_dwordx4 v133, v[18:21], s[18:19] offset:256
	v_cvt_pk_bf16_f32 v10, v10, v11
	v_cvt_pk_bf16_f32 v11, v12, v13
	v_cvt_pk_bf16_f32 v12, v14, v15
	v_cvt_pk_bf16_f32 v13, v16, v17
	v_cvt_pk_bf16_f32 v2, v2, v3
	v_cvt_pk_bf16_f32 v3, v4, v5
	v_cvt_pk_bf16_f32 v4, v6, v7
	v_cvt_pk_bf16_f32 v5, v8, v9
	v_add_u32_e32 v133, 0x1ce000, v130
	v_permlane16_swap_b32_e32 v10, v12
	v_permlane16_swap_b32_e32 v11, v13
	v_permlane16_swap_b32_e32 v2, v4
	v_permlane16_swap_b32_e32 v3, v5
	s_nop 0
	global_store_dwordx4 v133, v[10:13], s[18:19]
	global_store_dwordx4 v133, v[2:5], s[18:19] offset:256
	s_branch .LBB0_988
.Lep0_slow:
	v_or_b32_e32 v131, s6, v142
	v_lshlrev_b32_e32 v0, 5, v143
	v_lshlrev_b32_e32 v130, 2, v144
	v_add_u32_e32 v132, v131, v145
	v_or3_b32 v130, v0, v130, s8
	v_ashrrev_i32_e32 v133, 31, v132
	v_lshlrev_b64 v[134:135], 6, v[132:133]
	v_cmp_le_i32_e32 vcc, s39, v130
	v_subrev_u32_e32 v0, s39, v130
	s_and_saveexec_b64 s[6:7], vcc
	s_xor_b64 s[8:9], exec, s[6:7]
	s_cbranch_execz .LBB0_1032
	v_cmp_gt_i32_e64 s[6:7], s44, v0
	s_and_saveexec_b64 s[10:11], s[6:7]
	s_cbranch_execz .LBB0_1031
	v_lshl_add_u64 v[136:137], s[20:21], 0, v[134:135]
	v_pk_mul_f32 v[128:129], s[24:25], v[128:129]
	v_pk_mul_f32 v[126:127], s[16:17], v[126:127]
	v_lshl_add_u64 v[136:137], v[0:1], 2, v[136:137]
	global_store_dwordx4 v[136:137], v[126:129], off
